# final rmsnorm loop: the four final_norm gain vectors loaded once before the row loop instead of once per row behind vmcnt(0); loop-top wait removed
# speedup vs baseline: 1.0135x; 1.0032x over previous
; __device__ __forceinline__ float bflo(unsigned v) { return __uint_as_float(v << 16); }
; __device__ __forceinline__ float bfhi(unsigned v) { return __uint_as_float(v & 0xffff0000u); }
; __device__ __forceinline__ int opaque_tid() { int t = threadIdx.x & 255; asm volatile("" : "+v"(t)); return t; }
; __device__ __forceinline__ int opaque_bid() { int t = blockIdx.x * 2 + half_id(); asm volatile("" : "+s"(t)); return t; }
; __device__ __forceinline__ void phase_final(const Params& p, const WS& ws) {
;   const int tidf = opaque_tid();
;   const int lane = tidf & 63;
;   const int gw = opaque_bid() * 4 + (tidf >> 6), nw = NVB * 4;
; #pragma unroll 2
;   for (int r = gw; r < 8 * 2048; r += nw) {
;     const int b = r >> 11, s = r & 2047;
;     const size_t hoff = (size_t)(b * T_ + 16 + s) * 1024;
;     float4 v[4];
;     float ssum = 0.f;
; #pragma unroll
;     for (int i = 0; i < 4; ++i) {
;       const u32x2 hi = *(const u32x2*)(ws.HHI + hoff + i * 256 + lane * 4), lo = *(const u32x2*)(ws.HLO + hoff + i * 256 + lane * 4);
;       v[i] = make_float4(bflo(hi.x) + bflo(lo.x), bfhi(hi.x) + bfhi(lo.x), bflo(hi.y) + bflo(lo.y), bfhi(hi.y) + bfhi(lo.y));
;       ssum += v[i].x * v[i].x + v[i].y * v[i].y + v[i].z * v[i].z + v[i].w * v[i].w;
;     }
; #pragma unroll
;     for (int o = 1; o < 64; o <<= 1) ssum += __shfl_xor(ssum, o);
;     const float rstd = rsqrtf(ssum * (1.f / 1024.f) + EPS_);
; #pragma unroll
;     for (int i = 0; i < 4; ++i) {
;       const float4 g = *(const float4*)(p.final_norm + i * 256 + lane * 4);
.LBB0_1871:
	s_load_dwordx2 s[2:3], s[0:1], 0xc8
	s_load_dwordx2 s[8:9], s[0:1], 0xc0
	s_waitcnt vmcnt(6) lgkmcnt(0)
	v_mov_b32_e32 v0, s3
	v_mov_b32_e32 v1, s2
	v_readfirstlane_b32 s2, v175
	s_lshr_b32 s2, s2, 8
	v_readfirstlane_b32 s6, v1
	v_readfirstlane_b32 s7, v0
	v_mov_b32_e32 v0, s9
	v_mov_b32_e32 v1, s8
	s_add_i32 s2, s2, s69
	s_lshl_b32 s4, s2, 2
	s_waitcnt vmcnt(5)
	v_ashrrev_i32_e32 v6, 6, v186
	s_waitcnt vmcnt(2)
	v_add_u32_e32 v8, s4, v6
	s_movk_i32 s2, 0x4000
	v_cmp_gt_i32_e32 vcc, s2, v8
	s_and_saveexec_b64 s[2:3], vcc
	s_cbranch_execz .LBB0_1874
	v_lshlrev_b32_e32 v0, 2, v186
	v_and_b32_e32 v7, 0xfc, v0
	v_lshlrev_b32_e32 v4, 1, v7
	v_mov_b32_e32 v5, 0
	v_lshl_add_u64 v[0:1], s[6:7], 0, v[4:5]
	v_and_b32_e32 v4, 64, v191
	v_add_u32_e32 v4, 64, v4
	v_xor_b32_e32 v9, 1, v191
	v_cmp_lt_i32_e32 vcc, v9, v4
	v_xor_b32_e32 v10, 2, v191
	v_xor_b32_e32 v11, 4, v191
	v_cndmask_b32_e32 v9, v191, v9, vcc
	v_cmp_lt_i32_e32 vcc, v10, v4
	v_xor_b32_e32 v12, 8, v191
	v_xor_b32_e32 v13, 16, v191
	v_cndmask_b32_e32 v10, v191, v10, vcc
	v_cmp_lt_i32_e32 vcc, v11, v4
	v_xor_b32_e32 v14, 32, v191
	s_load_dwordx2 s[2:3], s[0:1], 0x110
	v_cndmask_b32_e32 v11, v191, v11, vcc
	v_cmp_lt_i32_e32 vcc, v12, v4
	s_load_dwordx2 s[0:1], s[0:1], 0xb8
	s_ashr_i32 s5, s4, 31
	v_cndmask_b32_e32 v12, v191, v12, vcc
	v_cmp_lt_i32_e32 vcc, v13, v4
	v_and_b32_e32 v15, 63, v186
	s_waitcnt lgkmcnt(0)
	s_lshl_b32 s2, s2, 3
	v_cndmask_b32_e32 v13, v191, v13, vcc
	v_cmp_lt_i32_e32 vcc, v14, v4
	s_mov_b64 s[6:7], 0x2040000
	s_ashr_i32 s3, s2, 31
	v_cndmask_b32_e32 v4, v191, v14, vcc
	v_lshlrev_b32_e32 v14, 2, v4
	v_lshlrev_b32_e32 v4, 2, v7
	v_ashrrev_i32_e32 v7, 31, v6
	v_lshl_add_u64 v[6:7], v[6:7], 0, s[4:5]
	v_lshlrev_b64 v[6:7], 12, v[6:7]
	v_lshl_or_b32 v6, v15, 4, v6
	v_lshl_add_u64 v[4:5], s[0:1], 0, v[4:5]
	v_lshl_add_u64 v[6:7], s[8:9], 0, v[6:7]
	s_mov_b64 s[0:1], 0x800
	v_lshl_add_u64 v[2:3], v[0:1], 0, s[6:7]
	v_lshlrev_b32_e32 v9, 2, v9
	v_lshlrev_b32_e32 v10, 2, v10
	v_lshlrev_b32_e32 v11, 2, v11
	v_lshlrev_b32_e32 v12, 2, v12
	v_lshlrev_b32_e32 v13, 2, v13
	v_lshl_add_u64 v[6:7], v[6:7], 0, s[0:1]
	s_lshl_b64 s[0:1], s[2:3], 12
	s_mov_b64 s[4:5], 0
	v_mov_b32_e32 v15, 0x358637bd
	s_mov_b32 s3, 0x800000
	s_movk_i32 s6, 0x3fff
	global_load_dwordx4 v[52:55], v[4:5], off
	global_load_dwordx4 v[56:59], v[4:5], off offset:1024
	global_load_dwordx4 v[60:63], v[4:5], off offset:2048
	global_load_dwordx4 v[64:67], v[4:5], off offset:3072
; __device__ __forceinline__ float bflo(unsigned v) { return __uint_as_float(v << 16); }
; __device__ __forceinline__ float bfhi(unsigned v) { return __uint_as_float(v & 0xffff0000u); }
; __device__ __forceinline__ void phase_final(const Params& p, const WS& ws) {
;     ...
;   for (int r = gw; r < 8 * 2048; r += nw) {
;     const int b = r >> 11, s = r & 2047;
;     const size_t hoff = (size_t)(b * T_ + 16 + s) * 1024;
;     float4 v[4];
;     float ssum = 0.f;
; #pragma unroll
;     for (int i = 0; i < 4; ++i) {
;       const u32x2 hi = *(const u32x2*)(ws.HHI + hoff + i * 256 + lane * 4), lo = *(const u32x2*)(ws.HLO + hoff + i * 256 + lane * 4);
;       v[i] = make_float4(bflo(hi.x) + bflo(lo.x), bfhi(hi.x) + bfhi(lo.x), bflo(hi.y) + bflo(lo.y), bfhi(hi.y) + bfhi(lo.y));
;       ssum += v[i].x * v[i].x + v[i].y * v[i].y + v[i].z * v[i].z + v[i].w * v[i].w;
;     }
; #pragma unroll
;     for (int o = 1; o < 64; o <<= 1) ssum += __shfl_xor(ssum, o);
;     const float rstd = rsqrtf(ssum * (1.f / 1024.f) + EPS_);
; #pragma unroll
;     for (int i = 0; i < 4; ++i) {
;       const float4 g = *(const float4*)(p.final_norm + i * 256 + lane * 4);
;       float4 o; o.x = v[i].x * rstd * g.x; o.y = v[i].y * rstd * g.y; o.z = v[i].z * rstd * g.z; o.w = v[i].w * rstd * g.w;
;       *(float4*)(p.out + (size_t)r * 1024 + i * 256 + lane * 4) = o;
;     }
;   }
.LBB0_1873:
	v_ashrrev_i32_e32 v16, 11, v8
	v_and_b32_e32 v17, 0x7ff, v8
	v_mul_i32_i24_e32 v16, 0x810, v16
	v_add3_u32 v16, v17, v16, 16
	v_ashrrev_i32_e32 v17, 31, v16
	v_lshlrev_b64 v[16:17], 11, v[16:17]
	v_lshl_add_u64 v[20:21], v[0:1], 0, v[16:17]
	v_lshl_add_u64 v[22:23], v[2:3], 0, v[16:17]
	global_load_dwordx2 v[24:25], v[20:21], off
	global_load_dwordx2 v[26:27], v[22:23], off
	global_load_dwordx2 v[28:29], v[20:21], off offset:512
	global_load_dwordx2 v[30:31], v[22:23], off offset:512
	global_load_dwordx2 v[32:33], v[20:21], off offset:1024
	global_load_dwordx2 v[34:35], v[22:23], off offset:1024
	global_load_dwordx2 v[36:37], v[20:21], off offset:1536
	global_load_dwordx2 v[38:39], v[22:23], off offset:1536
	v_add_u32_e32 v8, s2, v8
	s_waitcnt vmcnt(7)
	v_lshlrev_b32_e32 v20, 16, v24
	v_and_b32_e32 v21, 0xffff0000, v24
	s_waitcnt vmcnt(6)
	v_lshlrev_b32_e32 v22, 16, v26
	v_and_b32_e32 v23, 0xffff0000, v26
	v_lshlrev_b32_e32 v24, 16, v25
	v_and_b32_e32 v25, 0xffff0000, v25
	v_lshlrev_b32_e32 v26, 16, v27
	v_and_b32_e32 v27, 0xffff0000, v27
	s_waitcnt vmcnt(5)
	v_lshlrev_b32_e32 v40, 16, v28
	v_and_b32_e32 v41, 0xffff0000, v28
	s_waitcnt vmcnt(4)
	v_lshlrev_b32_e32 v42, 16, v30
	v_and_b32_e32 v43, 0xffff0000, v30
	v_lshlrev_b32_e32 v28, 16, v29
	v_and_b32_e32 v29, 0xffff0000, v29
	v_lshlrev_b32_e32 v30, 16, v31
	v_and_b32_e32 v31, 0xffff0000, v31
	s_waitcnt vmcnt(3)
	v_lshlrev_b32_e32 v44, 16, v32
	v_and_b32_e32 v45, 0xffff0000, v32
	s_waitcnt vmcnt(2)
	v_lshlrev_b32_e32 v46, 16, v34
	v_and_b32_e32 v47, 0xffff0000, v34
	v_lshlrev_b32_e32 v32, 16, v33
	v_and_b32_e32 v33, 0xffff0000, v33
	v_lshlrev_b32_e32 v34, 16, v35
	v_and_b32_e32 v35, 0xffff0000, v35
	s_waitcnt vmcnt(1)
	v_lshlrev_b32_e32 v48, 16, v36
	v_and_b32_e32 v49, 0xffff0000, v36
	s_waitcnt vmcnt(0)
	v_lshlrev_b32_e32 v50, 16, v38
	v_and_b32_e32 v51, 0xffff0000, v38
	v_lshlrev_b32_e32 v36, 16, v37
	v_and_b32_e32 v37, 0xffff0000, v37
	v_lshlrev_b32_e32 v38, 16, v39
	v_and_b32_e32 v39, 0xffff0000, v39
	v_pk_add_f32 v[20:21], v[20:21], v[22:23]
	v_pk_add_f32 v[22:23], v[24:25], v[26:27]
	v_pk_add_f32 v[24:25], v[40:41], v[42:43]
	v_pk_add_f32 v[26:27], v[28:29], v[30:31]
	v_pk_add_f32 v[28:29], v[44:45], v[46:47]
	v_pk_add_f32 v[30:31], v[32:33], v[34:35]
	v_pk_add_f32 v[32:33], v[48:49], v[50:51]
	v_pk_add_f32 v[34:35], v[36:37], v[38:39]
	v_mov_b32_e32 v38, v21
	v_mov_b32_e32 v39, v25
	v_mov_b32_e32 v36, v20
	v_mov_b32_e32 v37, v24
	v_mov_b32_e32 v46, v29
	v_mov_b32_e32 v47, v33
	v_pk_mul_f32 v[38:39], v[38:39], v[38:39]
	v_mov_b32_e32 v40, v22
	v_mov_b32_e32 v41, v26
	v_mov_b32_e32 v44, v28
	v_mov_b32_e32 v45, v32
	v_pk_mul_f32 v[46:47], v[46:47], v[46:47]
	v_pk_fma_f32 v[36:37], v[36:37], v[36:37], v[38:39]
	v_mov_b32_e32 v42, v23
	v_mov_b32_e32 v43, v27
	v_mov_b32_e32 v48, v30
	v_mov_b32_e32 v49, v34
	v_pk_fma_f32 v[38:39], v[44:45], v[44:45], v[46:47]
	v_pk_fma_f32 v[36:37], v[40:41], v[40:41], v[36:37]
	v_mov_b32_e32 v50, v31
	v_mov_b32_e32 v51, v35
	v_pk_fma_f32 v[38:39], v[48:49], v[48:49], v[38:39]
	v_pk_fma_f32 v[36:37], v[42:43], v[42:43], v[36:37]
	v_pk_fma_f32 v[38:39], v[50:51], v[50:51], v[38:39]
	v_add_f32_e32 v36, v36, v37
	v_add_f32_e32 v36, v36, v38
	v_add_f32_e32 v36, v36, v39
	ds_bpermute_b32 v37, v9, v36
	s_waitcnt lgkmcnt(0)
	v_add_f32_e32 v36, v36, v37
	ds_bpermute_b32 v37, v10, v36
	s_waitcnt lgkmcnt(0)
	v_add_f32_e32 v36, v36, v37
	ds_bpermute_b32 v37, v11, v36
	s_waitcnt lgkmcnt(0)
	v_add_f32_e32 v36, v36, v37
	ds_bpermute_b32 v37, v12, v36
	s_waitcnt lgkmcnt(0)
	v_add_f32_e32 v36, v36, v37
	ds_bpermute_b32 v37, v13, v36
	s_waitcnt lgkmcnt(0)
	v_add_f32_e32 v36, v36, v37
	ds_bpermute_b32 v37, v14, v36
	s_waitcnt lgkmcnt(0)
	v_add_f32_e32 v36, v36, v37
	v_fmamk_f32 v36, v36, 0x3a800000, v15
	v_mul_f32_e32 v37, 0x4b800000, v36
	v_cmp_gt_f32_e32 vcc, s3, v36
	s_nop 1
	v_cndmask_b32_e32 v36, v36, v37, vcc
	v_rsq_f32_e32 v36, v36
	s_nop 0
	v_mul_f32_e32 v37, 0x45800000, v36
	v_cndmask_b32_e32 v36, v36, v37, vcc
	v_pk_mul_f32 v[20:21], v[20:21], v[36:37] op_sel_hi:[1,0]
	v_pk_mul_f32 v[22:23], v[22:23], v[36:37] op_sel_hi:[1,0]
	v_pk_mul_f32 v[16:17], v[52:53], v[20:21]
	v_pk_mul_f32 v[18:19], v[54:55], v[22:23]
	global_store_dwordx4 v[6:7], v[16:19], off offset:-2048
	s_nop 1
	v_pk_mul_f32 v[20:21], v[24:25], v[36:37] op_sel_hi:[1,0]
	v_pk_mul_f32 v[22:23], v[26:27], v[36:37] op_sel_hi:[1,0]
	v_cmp_lt_i32_e32 vcc, s6, v8
	s_or_b64 s[4:5], vcc, s[4:5]
	v_pk_mul_f32 v[16:17], v[56:57], v[20:21]
	v_pk_mul_f32 v[18:19], v[58:59], v[22:23]
	global_store_dwordx4 v[6:7], v[16:19], off offset:-1024
	s_nop 1
	v_pk_mul_f32 v[20:21], v[28:29], v[36:37] op_sel_hi:[1,0]
	v_pk_mul_f32 v[22:23], v[30:31], v[36:37] op_sel_hi:[1,0]
	v_pk_mul_f32 v[16:17], v[60:61], v[20:21]
	v_pk_mul_f32 v[18:19], v[22:23], v[62:63]
	global_store_dwordx4 v[6:7], v[16:19], off
	s_nop 1
	v_pk_mul_f32 v[20:21], v[32:33], v[36:37] op_sel_hi:[1,0]
	v_pk_mul_f32 v[22:23], v[34:35], v[36:37] op_sel_hi:[1,0]
	v_pk_mul_f32 v[16:17], v[20:21], v[64:65]
	v_pk_mul_f32 v[18:19], v[22:23], v[66:67]
	global_store_dwordx4 v[6:7], v[16:19], off offset:1024
	s_nop 1
	v_lshl_add_u64 v[6:7], v[6:7], 0, s[0:1]
	s_andn2_b64 exec, exec, s[4:5]
	s_cbranch_execnz .LBB0_1873
